# v132 + grid barrier 4 replaced by an 8-workgroup row-block rendezvous; L2 write-back skipped only when all eight published XCC ids show one XCD (else released with buffer_wbl2 as before)
# speedup vs baseline: 1.0006x; 1.0006x over previous
.LBB0_653:
	s_or_b64 exec, exec, s[4:5]
	v_mov_b32_e32 v8, v225
	s_waitcnt lgkmcnt(0)
	v_cndmask_b32_e64 v0, 0, 1, s[16:17]
	s_barrier
	s_barrier
	s_mov_b32 s99, 0
	s_cmp_lg_u32 s24, 0x100
	s_cbranch_scc1 .Lb4_pub_done
	v_readfirstlane_b32 s87, v225
	s_nop 3
	s_cmp_lt_u32 s87, 64
	s_cbranch_scc0 .Lb4_pub_done
	s_and_b32 s87, s2, 7
	s_lshl_b32 s87, s87, 2
	s_bfe_u32 s86, s2, 0x20003
	s_add_i32 s87, s87, s86
	s_lshl_b32 s87, s87, 6
	s_add_u32 s88, s22, s87
	s_addc_u32 s89, s23, 0
	s_add_u32 s88, s88, 0x83800
	s_addc_u32 s89, s89, 0
	s_getreg_b32 s86, hwreg(HW_REG_XCC_ID, 0, 4)
	s_and_b32 s86, s86, 15
	s_lshl_b32 s86, 1, s86
	s_mov_b64 s[92:93], exec
	s_mov_b64 exec, 1
	v_mov_b32_e32 v250, 0
	v_mov_b32_e32 v251, s86
	v_mov_b32_e32 v252, 1
	global_atomic_or v250, v251, s[88:89] offset:16
	global_atomic_add v250, v252, s[88:89] offset:20
	s_mov_b64 exec, s[92:93]
.Lb4_pub_done:
	v_cmp_ne_u32_e64 s[8:9], 1, v0
	s_andn2_b64 vcc, exec, s[16:17]
	v_readfirstlane_b32 s6, v8
	s_cbranch_vccnz .LBB0_659

.LBB0_671:
	s_ashr_i32 s51, s50, 31
	s_lshl_b64 s[52:53], s[50:51], 20
	s_add_u32 s52, s10, s52
	s_addc_u32 s53, s11, s53
	s_and_b64 s[54:55], s[6:7], exec
	s_cselect_b32 s51, s53, s61
	s_cselect_b32 s57, s52, s60
	s_ashr_i32 s49, s48, 31
	s_lshl_b64 s[54:55], s[48:49], 20
	s_add_u32 s54, s34, s54
	s_addc_u32 s55, s35, s55
	s_and_b64 s[64:65], s[6:7], exec
	s_cselect_b32 s49, s55, s63
	s_cselect_b32 s77, s54, s62
	s_add_u32 s60, s60, 0x80080
	s_addc_u32 s61, s61, 0
	s_add_u32 s81, s62, 0x100
	v_mov_b32_e32 v0, 0
	s_addc_u32 s82, s63, 0
	s_mov_b32 s83, -2
	s_waitcnt lgkmcnt(0)
	v_mov_b32_e32 v1, v0
	v_mov_b32_e32 v2, v0
	v_mov_b32_e32 v3, v0
	v_mov_b32_e32 v4, v0
	v_mov_b32_e32 v5, v0
	v_mov_b32_e32 v6, v0
	v_mov_b32_e32 v7, v0
	v_mov_b32_e32 v16, v0
	v_mov_b32_e32 v17, v0
	v_mov_b32_e32 v18, v0
	v_mov_b32_e32 v19, v0
	v_mov_b32_e32 v20, v0
	v_mov_b32_e32 v21, v0
	v_mov_b32_e32 v22, v0
	v_mov_b32_e32 v23, v0
	v_mov_b32_e32 v32, v0
	v_mov_b32_e32 v33, v0
	v_mov_b32_e32 v34, v0
	v_mov_b32_e32 v35, v0
	v_mov_b32_e32 v36, v0
	v_mov_b32_e32 v37, v0
	v_mov_b32_e32 v38, v0
	v_mov_b32_e32 v39, v0
	v_mov_b32_e32 v48, v0
	v_mov_b32_e32 v49, v0
	v_mov_b32_e32 v50, v0
	v_mov_b32_e32 v51, v0
	v_mov_b32_e32 v52, v0
	v_mov_b32_e32 v53, v0
	v_mov_b32_e32 v54, v0
	v_mov_b32_e32 v55, v0
	v_mov_b32_e32 v8, v0
	v_mov_b32_e32 v9, v0
	v_mov_b32_e32 v10, v0
	v_mov_b32_e32 v11, v0
	v_mov_b32_e32 v12, v0
	v_mov_b32_e32 v13, v0
	v_mov_b32_e32 v14, v0
	v_mov_b32_e32 v15, v0
	v_mov_b32_e32 v24, v0
	v_mov_b32_e32 v25, v0
	v_mov_b32_e32 v26, v0
	v_mov_b32_e32 v27, v0
	v_mov_b32_e32 v28, v0
	v_mov_b32_e32 v29, v0
	v_mov_b32_e32 v30, v0
	v_mov_b32_e32 v31, v0
	v_mov_b32_e32 v40, v0
	v_mov_b32_e32 v41, v0
	v_mov_b32_e32 v42, v0
	v_mov_b32_e32 v43, v0
	v_mov_b32_e32 v44, v0
	v_mov_b32_e32 v45, v0
	v_mov_b32_e32 v46, v0
	v_mov_b32_e32 v47, v0
	v_mov_b32_e32 v56, v0
	v_mov_b32_e32 v57, v0
	v_mov_b32_e32 v58, v0
	v_mov_b32_e32 v59, v0
	v_mov_b32_e32 v60, v0
	v_mov_b32_e32 v61, v0
	v_mov_b32_e32 v62, v0
	v_mov_b32_e32 v63, v0
	v_mov_b32_e32 v64, v0
	v_mov_b32_e32 v65, v0
	v_mov_b32_e32 v66, v0
	v_mov_b32_e32 v67, v0
	v_mov_b32_e32 v68, v0
	v_mov_b32_e32 v69, v0
	v_mov_b32_e32 v70, v0
	v_mov_b32_e32 v71, v0
	v_mov_b32_e32 v80, v0
	v_mov_b32_e32 v81, v0
	v_mov_b32_e32 v82, v0
	v_mov_b32_e32 v83, v0
	v_mov_b32_e32 v84, v0
	v_mov_b32_e32 v85, v0
	v_mov_b32_e32 v86, v0
	v_mov_b32_e32 v87, v0
	v_mov_b32_e32 v96, v0
	v_mov_b32_e32 v97, v0
	v_mov_b32_e32 v98, v0
	v_mov_b32_e32 v99, v0
	v_mov_b32_e32 v100, v0
	v_mov_b32_e32 v101, v0
	v_mov_b32_e32 v102, v0
	v_mov_b32_e32 v103, v0
	v_mov_b32_e32 v112, v0
	v_mov_b32_e32 v113, v0
	v_mov_b32_e32 v114, v0
	v_mov_b32_e32 v115, v0
	v_mov_b32_e32 v116, v0
	v_mov_b32_e32 v117, v0
	v_mov_b32_e32 v118, v0
	v_mov_b32_e32 v119, v0
	v_mov_b32_e32 v72, v0
	v_mov_b32_e32 v73, v0
	v_mov_b32_e32 v74, v0
	v_mov_b32_e32 v75, v0
	v_mov_b32_e32 v76, v0
	v_mov_b32_e32 v77, v0
	v_mov_b32_e32 v78, v0
	v_mov_b32_e32 v79, v0
	v_mov_b32_e32 v88, v0
	v_mov_b32_e32 v89, v0
	v_mov_b32_e32 v90, v0
	v_mov_b32_e32 v91, v0
	v_mov_b32_e32 v92, v0
	v_mov_b32_e32 v93, v0
	v_mov_b32_e32 v94, v0
	v_mov_b32_e32 v95, v0
	v_mov_b32_e32 v104, v0
	v_mov_b32_e32 v105, v0
	v_mov_b32_e32 v106, v0
	v_mov_b32_e32 v107, v0
	v_mov_b32_e32 v108, v0
	v_mov_b32_e32 v109, v0
	v_mov_b32_e32 v110, v0
	v_mov_b32_e32 v111, v0
	v_mov_b32_e32 v120, v0
	v_mov_b32_e32 v121, v0
	v_mov_b32_e32 v122, v0
	v_mov_b32_e32 v123, v0
	v_mov_b32_e32 v124, v0
	v_mov_b32_e32 v125, v0
	v_mov_b32_e32 v126, v0
	v_mov_b32_e32 v127, v0
	s_nop 0
	s_nop 0
	s_nop 0
	s_nop 0
	s_nop 0
	s_nop 0
	s_nop 0
	s_nop 0
	s_nop 0
	s_nop 0
	s_nop 0
	s_nop 0
	s_nop 0
	s_nop 0
	s_nop 0

.Lp3_end:
	s_cmp_lg_u32 s24, 0x100
	s_cbranch_scc1 .Lb4_old
	s_and_b32 s87, s2, 7
	s_lshl_b32 s87, s87, 2
	s_bfe_u32 s86, s2, 0x20003
	s_add_i32 s87, s87, s86
	s_lshl_b32 s87, s87, 6
	s_add_u32 s88, s22, s87
	s_addc_u32 s89, s23, 0
	s_add_u32 s88, s88, 0x83800
	s_addc_u32 s89, s89, 0
	s_waitcnt vmcnt(0)
	s_barrier
	v_readfirstlane_b32 s87, v225
	s_nop 3
	s_cmp_lt_u32 s87, 64
	s_cbranch_scc0 .Lb4_join
	s_mov_b64 s[92:93], exec
	s_mov_b64 exec, 1
	v_mov_b32_e32 v0, 0
	global_load_dwordx2 v[2:3], v0, s[88:89] offset:16 sc1
	s_getreg_b32 s90, hwreg(HW_REG_XCC_ID, 0, 4)
	s_and_b32 s90, s90, 15
	s_lshl_b32 s90, 1, s90
	s_waitcnt vmcnt(0)
	v_readfirstlane_b32 s86, v2
	v_readfirstlane_b32 s87, v3
	s_nop 3
	s_cmp_lg_u32 s87, 8
	s_cbranch_scc1 .Lb4_wb
	s_cmp_eq_u32 s86, s90
	s_cbranch_scc1 .Lb4_nowb
.Lb4_wb:
	buffer_wbl2 sc1
	s_waitcnt vmcnt(0)
.Lb4_nowb:
	v_mov_b32_e32 v1, 1
	global_atomic_add v0, v1, s[88:89] offset:32
	s_mov_b32 s90, 0
.Lb4_poll:
	global_load_dword v2, v0, s[88:89] offset:32 sc1
	s_waitcnt vmcnt(0)
	v_readfirstlane_b32 s87, v2
	s_nop 3
	s_cmp_ge_u32 s87, 8
	s_cbranch_scc1 .Lb4_done
	s_sleep 1
	s_add_i32 s90, s90, 1
	s_cmp_lt_u32 s90, 0x8000
	s_cbranch_scc1 .Lb4_poll
.Lb4_done:
	buffer_inv sc1
	s_waitcnt vmcnt(0)
	s_mov_b64 exec, s[92:93]
.Lb4_join:
	s_barrier
	s_branch .Lb4_p4

.Lb4_p4:
	v_mov_b32_e32 v8, v225
	s_waitcnt lgkmcnt(0)
	s_barrier
	s_mov_b32 s99, 0
	s_and_b32 s87, s2, 7
	s_lshl_b32 s87, s87, 2
	s_bfe_u32 s86, s2, 0x20003
	s_add_i32 s87, s87, s86
	s_lshl_b32 s87, s87, 6
	s_add_u32 s88, s22, s87
	s_addc_u32 s89, s23, 0
	s_add_u32 s88, s88, 0x83800
	s_addc_u32 s89, s89, 0
	s_and_b64 vcc, exec, s[8:9]
	v_readfirstlane_b32 s6, v8
	s_cbranch_vccnz .LBB0_775
	s_ashr_i32 s3, s2, 31
	s_lshr_b32 s3, s3, 29
	s_add_i32 s16, s2, s3
	s_and_b32 s3, s16, -8
	s_sub_i32 s3, s2, s3
	s_cmp_gt_i32 s3, -1
	s_cbranch_scc0 .LBB0_772
	s_lshl_b32 s7, s3, 6
	s_ashr_i32 s4, s16, 3
	s_cbranch_execz .LBB0_773
	s_branch .LBB0_774

.LBB0_787:
	s_ashr_i32 s39, s38, 31
	s_lshl_b64 s[40:41], s[38:39], 20
	s_add_u32 s40, s12, s40
	s_addc_u32 s41, s13, s41
	s_and_b64 s[42:43], s[4:5], exec
	s_cselect_b32 s39, s41, s49
	s_cselect_b32 s45, s40, s48
	s_ashr_i32 s37, s36, 31
	s_lshl_b64 s[42:43], s[36:37], 20
	s_add_u32 s42, s28, s42
	s_addc_u32 s43, s29, s43
	s_and_b64 s[52:53], s[4:5], exec
	s_cselect_b32 s37, s43, s51
	s_cselect_b32 s66, s42, s50
	s_add_u32 s48, s48, 0x80080
	s_addc_u32 s49, s49, 0
	s_add_u32 s67, s50, 0x100
	v_mov_b32_e32 v0, 0
	s_addc_u32 s68, s51, 0
	s_mov_b32 s69, -2
	s_waitcnt lgkmcnt(0)
	v_mov_b32_e32 v1, v0
	v_mov_b32_e32 v2, v0
	v_mov_b32_e32 v3, v0
	v_mov_b32_e32 v4, v0
	v_mov_b32_e32 v5, v0
	v_mov_b32_e32 v6, v0
	v_mov_b32_e32 v7, v0
	v_mov_b32_e32 v16, v0
	v_mov_b32_e32 v17, v0
	v_mov_b32_e32 v18, v0
	v_mov_b32_e32 v19, v0
	v_mov_b32_e32 v20, v0
	v_mov_b32_e32 v21, v0
	v_mov_b32_e32 v22, v0
	v_mov_b32_e32 v23, v0
	v_mov_b32_e32 v32, v0
	v_mov_b32_e32 v33, v0
	v_mov_b32_e32 v34, v0
	v_mov_b32_e32 v35, v0
	v_mov_b32_e32 v36, v0
	v_mov_b32_e32 v37, v0
	v_mov_b32_e32 v38, v0
	v_mov_b32_e32 v39, v0
	v_mov_b32_e32 v48, v0
	v_mov_b32_e32 v49, v0
	v_mov_b32_e32 v50, v0
	v_mov_b32_e32 v51, v0
	v_mov_b32_e32 v52, v0
	v_mov_b32_e32 v53, v0
	v_mov_b32_e32 v54, v0
	v_mov_b32_e32 v55, v0
	v_mov_b32_e32 v8, v0
	v_mov_b32_e32 v9, v0
	v_mov_b32_e32 v10, v0
	v_mov_b32_e32 v11, v0
	v_mov_b32_e32 v12, v0
	v_mov_b32_e32 v13, v0
	v_mov_b32_e32 v14, v0
	v_mov_b32_e32 v15, v0
	v_mov_b32_e32 v24, v0
	v_mov_b32_e32 v25, v0
	v_mov_b32_e32 v26, v0
	v_mov_b32_e32 v27, v0
	v_mov_b32_e32 v28, v0
	v_mov_b32_e32 v29, v0
	v_mov_b32_e32 v30, v0
	v_mov_b32_e32 v31, v0
	v_mov_b32_e32 v40, v0
	v_mov_b32_e32 v41, v0
	v_mov_b32_e32 v42, v0
	v_mov_b32_e32 v43, v0
	v_mov_b32_e32 v44, v0
	v_mov_b32_e32 v45, v0
	v_mov_b32_e32 v46, v0
	v_mov_b32_e32 v47, v0
	v_mov_b32_e32 v56, v0
	v_mov_b32_e32 v57, v0
	v_mov_b32_e32 v58, v0
	v_mov_b32_e32 v59, v0
	v_mov_b32_e32 v60, v0
	v_mov_b32_e32 v61, v0
	v_mov_b32_e32 v62, v0
	v_mov_b32_e32 v63, v0
	v_mov_b32_e32 v64, v0
	v_mov_b32_e32 v65, v0
	v_mov_b32_e32 v66, v0
	v_mov_b32_e32 v67, v0
	v_mov_b32_e32 v68, v0
	v_mov_b32_e32 v69, v0
	v_mov_b32_e32 v70, v0
	v_mov_b32_e32 v71, v0
	v_mov_b32_e32 v80, v0
	v_mov_b32_e32 v81, v0
	v_mov_b32_e32 v82, v0
	v_mov_b32_e32 v83, v0
	v_mov_b32_e32 v84, v0
	v_mov_b32_e32 v85, v0
	v_mov_b32_e32 v86, v0
	v_mov_b32_e32 v87, v0
	v_mov_b32_e32 v96, v0
	v_mov_b32_e32 v97, v0
	v_mov_b32_e32 v98, v0
	v_mov_b32_e32 v99, v0
	v_mov_b32_e32 v100, v0
	v_mov_b32_e32 v101, v0
	v_mov_b32_e32 v102, v0
	v_mov_b32_e32 v103, v0
	v_mov_b32_e32 v112, v0
	v_mov_b32_e32 v113, v0
	v_mov_b32_e32 v114, v0
	v_mov_b32_e32 v115, v0
	v_mov_b32_e32 v116, v0
	v_mov_b32_e32 v117, v0
	v_mov_b32_e32 v118, v0
	v_mov_b32_e32 v119, v0
	v_mov_b32_e32 v72, v0
	v_mov_b32_e32 v73, v0
	v_mov_b32_e32 v74, v0
	v_mov_b32_e32 v75, v0
	v_mov_b32_e32 v76, v0
	v_mov_b32_e32 v77, v0
	v_mov_b32_e32 v78, v0
	v_mov_b32_e32 v79, v0
	v_mov_b32_e32 v88, v0
	v_mov_b32_e32 v89, v0
	v_mov_b32_e32 v90, v0
	v_mov_b32_e32 v91, v0
	v_mov_b32_e32 v92, v0
	v_mov_b32_e32 v93, v0
	v_mov_b32_e32 v94, v0
	v_mov_b32_e32 v95, v0
	v_mov_b32_e32 v104, v0
	v_mov_b32_e32 v105, v0
	v_mov_b32_e32 v106, v0
	v_mov_b32_e32 v107, v0
	v_mov_b32_e32 v108, v0
	v_mov_b32_e32 v109, v0
	v_mov_b32_e32 v110, v0
	v_mov_b32_e32 v111, v0
	v_mov_b32_e32 v120, v0
	v_mov_b32_e32 v121, v0
	v_mov_b32_e32 v122, v0
	v_mov_b32_e32 v123, v0
	v_mov_b32_e32 v124, v0
	v_mov_b32_e32 v125, v0
	v_mov_b32_e32 v126, v0
	v_mov_b32_e32 v127, v0
	s_nop 0
	s_nop 0
	s_nop 0
	s_nop 0
	s_nop 0
	s_nop 0
	s_nop 0
	s_nop 0
	s_nop 0
	s_nop 0
	s_nop 0
	s_nop 0
	s_nop 0
	s_nop 0
	s_nop 0
